# LRU work items draw their next queue ticket at item start (round trip overlaps the item); attention items unchanged
# speedup vs baseline: 1.0009x; 1.0009x over previous
.LBB0_1314:
	s_cmpk_gt_i32 s26, 0x41f
	s_mov_b64 s[0:1], -1
	s_cbranch_scc0 .LBB0_1340
	s_and_saveexec_b64 s[4:5], s[82:83]
	v_mov_b32_e32 v247, 1
	s_nop 0
	global_atomic_add v247, v189, v247, s[8:9] sc0
	s_or_b64 exec, exec, s[4:5]
	s_add_i32 s1, s26, 0xfffffbe0
	s_cmpk_gt_u32 s1, 0x1ff
	s_cselect_b64 s[6:7], -1, 0
	s_cmpk_lt_u32 s1, 0x200
	v_mov_b32_e32 v2, v0
	s_cselect_b64 s[4:5], -1, 0
	s_mov_b64 s[12:13], -1
	s_and_b64 vcc, exec, s[6:7]
	s_barrier
	s_cbranch_vccnz .LBB0_1323
	s_lshr_b32 s0, s1, 7
	s_and_b32 s27, s1, 0x7f
	s_lshl_b32 s34, s1, 6
	s_mov_b32 s69, 64
	s_cbranch_execz .LBB0_1324

.LBB0_1335:
	s_and_saveexec_b64 s[0:1], s[82:83]
	s_cbranch_execz .LBB0_1339
	v_mov_b32_e32 v3, s3
	s_waitcnt vmcnt(0)
	ds_write_b32 v3, v247
